# v44: prep pool_fold inner loop keeps four iterations of loads in flight (rotating register sets, peeled tail)
# baseline (speedup 1.0000x reference)
.LBB0_315:
	s_and_b32 s2, s10, 0x3c0
	v_add_u32_e32 v0, s2, v13
	s_lshl_b32 s2, s22, 2
	s_and_b32 s2, s2, 0x100
	v_lshl_or_b32 v64, v12, 2, s2
	s_ashr_i32 s2, s28, 5
	s_ashr_i32 s3, s2, 31
	s_lshl_b64 s[4:5], s[2:3], 16
	s_lshl_b32 s2, s2, 7
	s_ashr_i32 s3, s2, 31
	s_lshl_b64 s[2:3], s[2:3], 2
	v_ashrrev_i32_e32 v1, 31, v0
	s_add_u32 s2, s6, s2
	v_lshlrev_b64 v[0:1], 12, v[0:1]
	s_addc_u32 s3, s7, s3
	v_lshl_add_u64 v[8:9], s[2:3], 0, v[0:1]
	s_add_u32 s2, s12, s4
	s_addc_u32 s3, s13, s5
	v_mov_b32_e32 v0, 0
	v_lshl_add_u64 v[10:11], s[2:3], 0, v[64:65]
	s_mov_b64 s[4:5], 0
	v_mov_b32_e32 v1, v0
	v_mov_b32_e32 v4, v0
	v_mov_b32_e32 v5, v0
	v_mov_b32_e32 v2, v0
	v_mov_b32_e32 v3, v0
	v_mov_b32_e32 v6, v0
	v_mov_b32_e32 v7, v0
	v_mov_b32_e32 v246, v10
	v_mov_b32_e32 v247, v11
	v_add_co_u32_e32 v248, vcc, 0x1000, v8
	s_nop 1
	v_addc_co_u32_e32 v249, vcc, 0, v9, vcc
	v_add_co_u32_e32 v250, vcc, 0x3000, v8
	s_nop 1
	v_addc_co_u32_e32 v251, vcc, 0, v9, vcc
	v_add_co_u32_e32 v252, vcc, 0x5000, v8
	s_nop 1
	v_addc_co_u32_e32 v253, vcc, 0, v9, vcc
	v_add_co_u32_e32 v98, vcc, 0x7000, v8
	s_nop 1
	v_addc_co_u32_e32 v99, vcc, 0, v9, vcc
	global_load_dword v100, v[246:247], off offset:-1024
	global_load_dword v101, v[246:247], off offset:-512
	global_load_dword v102, v[246:247], off
	global_load_dword v103, v[246:247], off offset:512
	global_load_dwordx4 v[104:107], v[248:249], off offset:-4096
	global_load_dwordx4 v[128:131], v[248:249], off
	global_load_dwordx4 v[132:135], v[250:251], off offset:-4096
	global_load_dwordx4 v[108:111], v[250:251], off
	global_load_dwordx4 v[112:115], v[252:253], off offset:-4096
	global_load_dwordx4 v[116:119], v[252:253], off
	global_load_dwordx4 v[120:123], v[98:99], off offset:-4096
	global_load_dwordx4 v[124:127], v[98:99], off
	v_add_co_u32_e32 v246, vcc, 0x800, v246
	s_nop 1
	v_addc_co_u32_e32 v247, vcc, 0, v247, vcc
	v_add_co_u32_e32 v248, vcc, 0x10, v248
	s_nop 1
	v_addc_co_u32_e32 v249, vcc, 0, v249, vcc
	v_add_co_u32_e32 v250, vcc, 0x10, v250
	s_nop 1
	v_addc_co_u32_e32 v251, vcc, 0, v251, vcc
	v_add_co_u32_e32 v252, vcc, 0x10, v252
	s_nop 1
	v_addc_co_u32_e32 v253, vcc, 0, v253, vcc
	v_add_co_u32_e32 v98, vcc, 0x10, v98
	s_nop 1
	v_addc_co_u32_e32 v99, vcc, 0, v99, vcc
	global_load_dword v136, v[246:247], off offset:-1024
	global_load_dword v137, v[246:247], off offset:-512
	global_load_dword v138, v[246:247], off
	global_load_dword v139, v[246:247], off offset:512
	global_load_dwordx4 v[140:143], v[248:249], off offset:-4096
	global_load_dwordx4 v[164:167], v[248:249], off
	global_load_dwordx4 v[168:171], v[250:251], off offset:-4096
	global_load_dwordx4 v[144:147], v[250:251], off
	global_load_dwordx4 v[148:151], v[252:253], off offset:-4096
	global_load_dwordx4 v[152:155], v[252:253], off
	global_load_dwordx4 v[156:159], v[98:99], off offset:-4096
	global_load_dwordx4 v[160:163], v[98:99], off
	v_add_co_u32_e32 v246, vcc, 0x800, v246
	s_nop 1
	v_addc_co_u32_e32 v247, vcc, 0, v247, vcc
	v_add_co_u32_e32 v248, vcc, 0x10, v248
	s_nop 1
	v_addc_co_u32_e32 v249, vcc, 0, v249, vcc
	v_add_co_u32_e32 v250, vcc, 0x10, v250
	s_nop 1
	v_addc_co_u32_e32 v251, vcc, 0, v251, vcc
	v_add_co_u32_e32 v252, vcc, 0x10, v252
	s_nop 1
	v_addc_co_u32_e32 v253, vcc, 0, v253, vcc
	v_add_co_u32_e32 v98, vcc, 0x10, v98
	s_nop 1
	v_addc_co_u32_e32 v99, vcc, 0, v99, vcc
	global_load_dword v174, v[246:247], off offset:-1024
	global_load_dword v175, v[246:247], off offset:-512
	global_load_dword v176, v[246:247], off
	global_load_dword v177, v[246:247], off offset:512
	global_load_dwordx4 v[178:181], v[248:249], off offset:-4096
	global_load_dwordx4 v[202:205], v[248:249], off
	global_load_dwordx4 v[206:209], v[250:251], off offset:-4096
	global_load_dwordx4 v[182:185], v[250:251], off
	global_load_dwordx4 v[186:189], v[252:253], off offset:-4096
	global_load_dwordx4 v[190:193], v[252:253], off
	global_load_dwordx4 v[194:197], v[98:99], off offset:-4096
	global_load_dwordx4 v[198:201], v[98:99], off
	v_add_co_u32_e32 v246, vcc, 0x800, v246
	s_nop 1
	v_addc_co_u32_e32 v247, vcc, 0, v247, vcc
	v_add_co_u32_e32 v248, vcc, 0x10, v248
	s_nop 1
	v_addc_co_u32_e32 v249, vcc, 0, v249, vcc
	v_add_co_u32_e32 v250, vcc, 0x10, v250
	s_nop 1
	v_addc_co_u32_e32 v251, vcc, 0, v251, vcc
	v_add_co_u32_e32 v252, vcc, 0x10, v252
	s_nop 1
	v_addc_co_u32_e32 v253, vcc, 0, v253, vcc
	v_add_co_u32_e32 v98, vcc, 0x10, v98
	s_nop 1
	v_addc_co_u32_e32 v99, vcc, 0, v99, vcc
	global_load_dword v210, v[246:247], off offset:-1024
	global_load_dword v211, v[246:247], off offset:-512
	global_load_dword v212, v[246:247], off
	global_load_dword v213, v[246:247], off offset:512
	global_load_dwordx4 v[214:217], v[248:249], off offset:-4096
	global_load_dwordx4 v[238:241], v[248:249], off
	global_load_dwordx4 v[242:245], v[250:251], off offset:-4096
	global_load_dwordx4 v[218:221], v[250:251], off
	global_load_dwordx4 v[222:225], v[252:253], off offset:-4096
	global_load_dwordx4 v[226:229], v[252:253], off
	global_load_dwordx4 v[230:233], v[98:99], off offset:-4096
	global_load_dwordx4 v[234:237], v[98:99], off
	v_add_co_u32_e32 v246, vcc, 0x800, v246
	s_nop 1
	v_addc_co_u32_e32 v247, vcc, 0, v247, vcc
	v_add_co_u32_e32 v248, vcc, 0x10, v248
	s_nop 1
	v_addc_co_u32_e32 v249, vcc, 0, v249, vcc
	v_add_co_u32_e32 v250, vcc, 0x10, v250
	s_nop 1
	v_addc_co_u32_e32 v251, vcc, 0, v251, vcc
	v_add_co_u32_e32 v252, vcc, 0x10, v252
	s_nop 1
	v_addc_co_u32_e32 v253, vcc, 0, v253, vcc
	v_add_co_u32_e32 v98, vcc, 0x10, v98
	s_nop 1
	v_addc_co_u32_e32 v99, vcc, 0, v99, vcc
	s_mov_b32 s4, 0
.LBB0_316:
	s_waitcnt vmcnt(36)
	v_mov_b32_e32 v48, v100
	v_mov_b32_e32 v50, v101
	v_mov_b32_e32 v52, v102
	v_mov_b32_e32 v54, v103
	v_mov_b32_e32 v16, v104
	v_mov_b32_e32 v17, v105
	v_mov_b32_e32 v18, v106
	v_mov_b32_e32 v19, v107
	v_mov_b32_e32 v20, v108
	v_mov_b32_e32 v21, v109
	v_mov_b32_e32 v22, v110
	v_mov_b32_e32 v23, v111
	v_mov_b32_e32 v24, v112
	v_mov_b32_e32 v25, v113
	v_mov_b32_e32 v26, v114
	v_mov_b32_e32 v27, v115
	v_mov_b32_e32 v28, v116
	v_mov_b32_e32 v29, v117
	v_mov_b32_e32 v30, v118
	v_mov_b32_e32 v31, v119
	v_mov_b32_e32 v32, v120
	v_mov_b32_e32 v33, v121
	v_mov_b32_e32 v34, v122
	v_mov_b32_e32 v35, v123
	v_mov_b32_e32 v36, v124
	v_mov_b32_e32 v37, v125
	v_mov_b32_e32 v38, v126
	v_mov_b32_e32 v39, v127
	v_mov_b32_e32 v40, v128
	v_mov_b32_e32 v41, v129
	v_mov_b32_e32 v42, v130
	v_mov_b32_e32 v43, v131
	v_mov_b32_e32 v44, v132
	v_mov_b32_e32 v45, v133
	v_mov_b32_e32 v46, v134
	v_mov_b32_e32 v47, v135
	global_load_dword v100, v[246:247], off offset:-1024
	global_load_dword v101, v[246:247], off offset:-512
	global_load_dword v102, v[246:247], off
	global_load_dword v103, v[246:247], off offset:512
	global_load_dwordx4 v[104:107], v[248:249], off offset:-4096
	global_load_dwordx4 v[128:131], v[248:249], off
	global_load_dwordx4 v[132:135], v[250:251], off offset:-4096
	global_load_dwordx4 v[108:111], v[250:251], off
	global_load_dwordx4 v[112:115], v[252:253], off offset:-4096
	global_load_dwordx4 v[116:119], v[252:253], off
	global_load_dwordx4 v[120:123], v[98:99], off offset:-4096
	global_load_dwordx4 v[124:127], v[98:99], off
	v_add_co_u32_e32 v246, vcc, 0x800, v246
	s_nop 1
	v_addc_co_u32_e32 v247, vcc, 0, v247, vcc
	v_add_co_u32_e32 v248, vcc, 0x10, v248
	s_nop 1
	v_addc_co_u32_e32 v249, vcc, 0, v249, vcc
	v_add_co_u32_e32 v250, vcc, 0x10, v250
	s_nop 1
	v_addc_co_u32_e32 v251, vcc, 0, v251, vcc
	v_add_co_u32_e32 v252, vcc, 0x10, v252
	s_nop 1
	v_addc_co_u32_e32 v253, vcc, 0, v253, vcc
	v_add_co_u32_e32 v98, vcc, 0x10, v98
	s_nop 1
	v_addc_co_u32_e32 v99, vcc, 0, v99, vcc
	v_mov_b32_e32 v56, v16
	v_mov_b32_e32 v16, v18
	v_mov_b32_e32 v59, v20
	v_mov_b32_e32 v60, v24
	v_mov_b32_e32 v61, v28
	v_mov_b32_e32 v62, v32
	v_mov_b32_e32 v63, v36
	v_mov_b32_e32 v57, v40
	v_mov_b32_e32 v58, v44
	v_mov_b32_e32 v28, v25
	v_mov_b32_e32 v36, v33
	v_pk_fma_f32 v[6:7], v[48:49], v[60:61], v[6:7] op_sel_hi:[0,1,1]
	v_pk_fma_f32 v[0:1], v[48:49], v[62:63], v[0:1] op_sel_hi:[0,1,1]
	v_mov_b32_e32 v40, v17
	v_mov_b32_e32 v20, v45
	v_pk_fma_f32 v[4:5], v[48:49], v[56:57], v[4:5] op_sel_hi:[0,1,1]
	v_pk_fma_f32 v[2:3], v[48:49], v[58:59], v[2:3] op_sel_hi:[0,1,1]
	v_mov_b32_e32 v25, v22
	v_mov_b32_e32 v32, v26
	v_mov_b32_e32 v33, v30
	v_mov_b32_e32 v66, v34
	v_mov_b32_e32 v67, v38
	v_mov_b32_e32 v17, v42
	v_mov_b32_e32 v24, v46
	v_pk_fma_f32 v[6:7], v[50:51], v[28:29], v[6:7] op_sel_hi:[0,1,1]
	v_pk_fma_f32 v[0:1], v[50:51], v[36:37], v[0:1] op_sel_hi:[0,1,1]
	v_pk_fma_f32 v[4:5], v[50:51], v[40:41], v[4:5] op_sel_hi:[0,1,1]
	v_pk_fma_f32 v[2:3], v[50:51], v[20:21], v[2:3] op_sel_hi:[0,1,1]
	v_mov_b32_e32 v30, v27
	v_mov_b32_e32 v38, v35
	v_mov_b32_e32 v42, v19
	v_mov_b32_e32 v22, v47
	v_pk_fma_f32 v[6:7], v[52:53], v[32:33], v[6:7] op_sel_hi:[0,1,1]
	v_pk_fma_f32 v[0:1], v[52:53], v[66:67], v[0:1] op_sel_hi:[0,1,1]
	v_pk_fma_f32 v[4:5], v[52:53], v[16:17], v[4:5] op_sel_hi:[0,1,1]
	v_pk_fma_f32 v[2:3], v[52:53], v[24:25], v[2:3] op_sel_hi:[0,1,1]
	v_pk_fma_f32 v[6:7], v[54:55], v[30:31], v[6:7] op_sel_hi:[0,1,1]
	v_pk_fma_f32 v[0:1], v[54:55], v[38:39], v[0:1] op_sel_hi:[0,1,1]
	v_pk_fma_f32 v[4:5], v[54:55], v[42:43], v[4:5] op_sel_hi:[0,1,1]
	v_pk_fma_f32 v[2:3], v[54:55], v[22:23], v[2:3] op_sel_hi:[0,1,1]
	s_waitcnt vmcnt(36)
	v_mov_b32_e32 v48, v136
	v_mov_b32_e32 v50, v137
	v_mov_b32_e32 v52, v138
	v_mov_b32_e32 v54, v139
	v_mov_b32_e32 v16, v140
	v_mov_b32_e32 v17, v141
	v_mov_b32_e32 v18, v142
	v_mov_b32_e32 v19, v143
	v_mov_b32_e32 v20, v144
	v_mov_b32_e32 v21, v145
	v_mov_b32_e32 v22, v146
	v_mov_b32_e32 v23, v147
	v_mov_b32_e32 v24, v148
	v_mov_b32_e32 v25, v149
	v_mov_b32_e32 v26, v150
	v_mov_b32_e32 v27, v151
	v_mov_b32_e32 v28, v152
	v_mov_b32_e32 v29, v153
	v_mov_b32_e32 v30, v154
	v_mov_b32_e32 v31, v155
	v_mov_b32_e32 v32, v156
	v_mov_b32_e32 v33, v157
	v_mov_b32_e32 v34, v158
	v_mov_b32_e32 v35, v159
	v_mov_b32_e32 v36, v160
	v_mov_b32_e32 v37, v161
	v_mov_b32_e32 v38, v162
	v_mov_b32_e32 v39, v163
	v_mov_b32_e32 v40, v164
	v_mov_b32_e32 v41, v165
	v_mov_b32_e32 v42, v166
	v_mov_b32_e32 v43, v167
	v_mov_b32_e32 v44, v168
	v_mov_b32_e32 v45, v169
	v_mov_b32_e32 v46, v170
	v_mov_b32_e32 v47, v171
	global_load_dword v136, v[246:247], off offset:-1024
	global_load_dword v137, v[246:247], off offset:-512
	global_load_dword v138, v[246:247], off
	global_load_dword v139, v[246:247], off offset:512
	global_load_dwordx4 v[140:143], v[248:249], off offset:-4096
	global_load_dwordx4 v[164:167], v[248:249], off
	global_load_dwordx4 v[168:171], v[250:251], off offset:-4096
	global_load_dwordx4 v[144:147], v[250:251], off
	global_load_dwordx4 v[148:151], v[252:253], off offset:-4096
	global_load_dwordx4 v[152:155], v[252:253], off
	global_load_dwordx4 v[156:159], v[98:99], off offset:-4096
	global_load_dwordx4 v[160:163], v[98:99], off
	v_add_co_u32_e32 v246, vcc, 0x800, v246
	s_nop 1
	v_addc_co_u32_e32 v247, vcc, 0, v247, vcc
	v_add_co_u32_e32 v248, vcc, 0x10, v248
	s_nop 1
	v_addc_co_u32_e32 v249, vcc, 0, v249, vcc
	v_add_co_u32_e32 v250, vcc, 0x10, v250
	s_nop 1
	v_addc_co_u32_e32 v251, vcc, 0, v251, vcc
	v_add_co_u32_e32 v252, vcc, 0x10, v252
	s_nop 1
	v_addc_co_u32_e32 v253, vcc, 0, v253, vcc
	v_add_co_u32_e32 v98, vcc, 0x10, v98
	s_nop 1
	v_addc_co_u32_e32 v99, vcc, 0, v99, vcc
	v_mov_b32_e32 v56, v16
	v_mov_b32_e32 v16, v18
	v_mov_b32_e32 v59, v20
	v_mov_b32_e32 v60, v24
	v_mov_b32_e32 v61, v28
	v_mov_b32_e32 v62, v32
	v_mov_b32_e32 v63, v36
	v_mov_b32_e32 v57, v40
	v_mov_b32_e32 v58, v44
	v_mov_b32_e32 v28, v25
	v_mov_b32_e32 v36, v33
	v_pk_fma_f32 v[6:7], v[48:49], v[60:61], v[6:7] op_sel_hi:[0,1,1]
	v_pk_fma_f32 v[0:1], v[48:49], v[62:63], v[0:1] op_sel_hi:[0,1,1]
	v_mov_b32_e32 v40, v17
	v_mov_b32_e32 v20, v45
	v_pk_fma_f32 v[4:5], v[48:49], v[56:57], v[4:5] op_sel_hi:[0,1,1]
	v_pk_fma_f32 v[2:3], v[48:49], v[58:59], v[2:3] op_sel_hi:[0,1,1]
	v_mov_b32_e32 v25, v22
	v_mov_b32_e32 v32, v26
	v_mov_b32_e32 v33, v30
	v_mov_b32_e32 v66, v34
	v_mov_b32_e32 v67, v38
	v_mov_b32_e32 v17, v42
	v_mov_b32_e32 v24, v46
	v_pk_fma_f32 v[6:7], v[50:51], v[28:29], v[6:7] op_sel_hi:[0,1,1]
	v_pk_fma_f32 v[0:1], v[50:51], v[36:37], v[0:1] op_sel_hi:[0,1,1]
	v_pk_fma_f32 v[4:5], v[50:51], v[40:41], v[4:5] op_sel_hi:[0,1,1]
	v_pk_fma_f32 v[2:3], v[50:51], v[20:21], v[2:3] op_sel_hi:[0,1,1]
	v_mov_b32_e32 v30, v27
	v_mov_b32_e32 v38, v35
	v_mov_b32_e32 v42, v19
	v_mov_b32_e32 v22, v47
	v_pk_fma_f32 v[6:7], v[52:53], v[32:33], v[6:7] op_sel_hi:[0,1,1]
	v_pk_fma_f32 v[0:1], v[52:53], v[66:67], v[0:1] op_sel_hi:[0,1,1]
	v_pk_fma_f32 v[4:5], v[52:53], v[16:17], v[4:5] op_sel_hi:[0,1,1]
	v_pk_fma_f32 v[2:3], v[52:53], v[24:25], v[2:3] op_sel_hi:[0,1,1]
	v_pk_fma_f32 v[6:7], v[54:55], v[30:31], v[6:7] op_sel_hi:[0,1,1]
	v_pk_fma_f32 v[0:1], v[54:55], v[38:39], v[0:1] op_sel_hi:[0,1,1]
	v_pk_fma_f32 v[4:5], v[54:55], v[42:43], v[4:5] op_sel_hi:[0,1,1]
	v_pk_fma_f32 v[2:3], v[54:55], v[22:23], v[2:3] op_sel_hi:[0,1,1]
	s_waitcnt vmcnt(36)
	v_mov_b32_e32 v48, v174
	v_mov_b32_e32 v50, v175
	v_mov_b32_e32 v52, v176
	v_mov_b32_e32 v54, v177
	v_mov_b32_e32 v16, v178
	v_mov_b32_e32 v17, v179
	v_mov_b32_e32 v18, v180
	v_mov_b32_e32 v19, v181
	v_mov_b32_e32 v20, v182
	v_mov_b32_e32 v21, v183
	v_mov_b32_e32 v22, v184
	v_mov_b32_e32 v23, v185
	v_mov_b32_e32 v24, v186
	v_mov_b32_e32 v25, v187
	v_mov_b32_e32 v26, v188
	v_mov_b32_e32 v27, v189
	v_mov_b32_e32 v28, v190
	v_mov_b32_e32 v29, v191
	v_mov_b32_e32 v30, v192
	v_mov_b32_e32 v31, v193
	v_mov_b32_e32 v32, v194
	v_mov_b32_e32 v33, v195
	v_mov_b32_e32 v34, v196
	v_mov_b32_e32 v35, v197
	v_mov_b32_e32 v36, v198
	v_mov_b32_e32 v37, v199
	v_mov_b32_e32 v38, v200
	v_mov_b32_e32 v39, v201
	v_mov_b32_e32 v40, v202
	v_mov_b32_e32 v41, v203
	v_mov_b32_e32 v42, v204
	v_mov_b32_e32 v43, v205
	v_mov_b32_e32 v44, v206
	v_mov_b32_e32 v45, v207
	v_mov_b32_e32 v46, v208
	v_mov_b32_e32 v47, v209
	global_load_dword v174, v[246:247], off offset:-1024
	global_load_dword v175, v[246:247], off offset:-512
	global_load_dword v176, v[246:247], off
	global_load_dword v177, v[246:247], off offset:512
	global_load_dwordx4 v[178:181], v[248:249], off offset:-4096
	global_load_dwordx4 v[202:205], v[248:249], off
	global_load_dwordx4 v[206:209], v[250:251], off offset:-4096
	global_load_dwordx4 v[182:185], v[250:251], off
	global_load_dwordx4 v[186:189], v[252:253], off offset:-4096
	global_load_dwordx4 v[190:193], v[252:253], off
	global_load_dwordx4 v[194:197], v[98:99], off offset:-4096
	global_load_dwordx4 v[198:201], v[98:99], off
	v_add_co_u32_e32 v246, vcc, 0x800, v246
	s_nop 1
	v_addc_co_u32_e32 v247, vcc, 0, v247, vcc
	v_add_co_u32_e32 v248, vcc, 0x10, v248
	s_nop 1
	v_addc_co_u32_e32 v249, vcc, 0, v249, vcc
	v_add_co_u32_e32 v250, vcc, 0x10, v250
	s_nop 1
	v_addc_co_u32_e32 v251, vcc, 0, v251, vcc
	v_add_co_u32_e32 v252, vcc, 0x10, v252
	s_nop 1
	v_addc_co_u32_e32 v253, vcc, 0, v253, vcc
	v_add_co_u32_e32 v98, vcc, 0x10, v98
	s_nop 1
	v_addc_co_u32_e32 v99, vcc, 0, v99, vcc
	v_mov_b32_e32 v56, v16
	v_mov_b32_e32 v16, v18
	v_mov_b32_e32 v59, v20
	v_mov_b32_e32 v60, v24
	v_mov_b32_e32 v61, v28
	v_mov_b32_e32 v62, v32
	v_mov_b32_e32 v63, v36
	v_mov_b32_e32 v57, v40
	v_mov_b32_e32 v58, v44
	v_mov_b32_e32 v28, v25
	v_mov_b32_e32 v36, v33
	v_pk_fma_f32 v[6:7], v[48:49], v[60:61], v[6:7] op_sel_hi:[0,1,1]
	v_pk_fma_f32 v[0:1], v[48:49], v[62:63], v[0:1] op_sel_hi:[0,1,1]
	v_mov_b32_e32 v40, v17
	v_mov_b32_e32 v20, v45
	v_pk_fma_f32 v[4:5], v[48:49], v[56:57], v[4:5] op_sel_hi:[0,1,1]
	v_pk_fma_f32 v[2:3], v[48:49], v[58:59], v[2:3] op_sel_hi:[0,1,1]
	v_mov_b32_e32 v25, v22
	v_mov_b32_e32 v32, v26
	v_mov_b32_e32 v33, v30
	v_mov_b32_e32 v66, v34
	v_mov_b32_e32 v67, v38
	v_mov_b32_e32 v17, v42
	v_mov_b32_e32 v24, v46
	v_pk_fma_f32 v[6:7], v[50:51], v[28:29], v[6:7] op_sel_hi:[0,1,1]
	v_pk_fma_f32 v[0:1], v[50:51], v[36:37], v[0:1] op_sel_hi:[0,1,1]
	v_pk_fma_f32 v[4:5], v[50:51], v[40:41], v[4:5] op_sel_hi:[0,1,1]
	v_pk_fma_f32 v[2:3], v[50:51], v[20:21], v[2:3] op_sel_hi:[0,1,1]
	v_mov_b32_e32 v30, v27
	v_mov_b32_e32 v38, v35
	v_mov_b32_e32 v42, v19
	v_mov_b32_e32 v22, v47
	v_pk_fma_f32 v[6:7], v[52:53], v[32:33], v[6:7] op_sel_hi:[0,1,1]
	v_pk_fma_f32 v[0:1], v[52:53], v[66:67], v[0:1] op_sel_hi:[0,1,1]
	v_pk_fma_f32 v[4:5], v[52:53], v[16:17], v[4:5] op_sel_hi:[0,1,1]
	v_pk_fma_f32 v[2:3], v[52:53], v[24:25], v[2:3] op_sel_hi:[0,1,1]
	v_pk_fma_f32 v[6:7], v[54:55], v[30:31], v[6:7] op_sel_hi:[0,1,1]
	v_pk_fma_f32 v[0:1], v[54:55], v[38:39], v[0:1] op_sel_hi:[0,1,1]
	v_pk_fma_f32 v[4:5], v[54:55], v[42:43], v[4:5] op_sel_hi:[0,1,1]
	v_pk_fma_f32 v[2:3], v[54:55], v[22:23], v[2:3] op_sel_hi:[0,1,1]
	s_waitcnt vmcnt(36)
	v_mov_b32_e32 v48, v210
	v_mov_b32_e32 v50, v211
	v_mov_b32_e32 v52, v212
	v_mov_b32_e32 v54, v213
	v_mov_b32_e32 v16, v214
	v_mov_b32_e32 v17, v215
	v_mov_b32_e32 v18, v216
	v_mov_b32_e32 v19, v217
	v_mov_b32_e32 v20, v218
	v_mov_b32_e32 v21, v219
	v_mov_b32_e32 v22, v220
	v_mov_b32_e32 v23, v221
	v_mov_b32_e32 v24, v222
	v_mov_b32_e32 v25, v223
	v_mov_b32_e32 v26, v224
	v_mov_b32_e32 v27, v225
	v_mov_b32_e32 v28, v226
	v_mov_b32_e32 v29, v227
	v_mov_b32_e32 v30, v228
	v_mov_b32_e32 v31, v229
	v_mov_b32_e32 v32, v230
	v_mov_b32_e32 v33, v231
	v_mov_b32_e32 v34, v232
	v_mov_b32_e32 v35, v233
	v_mov_b32_e32 v36, v234
	v_mov_b32_e32 v37, v235
	v_mov_b32_e32 v38, v236
	v_mov_b32_e32 v39, v237
	v_mov_b32_e32 v40, v238
	v_mov_b32_e32 v41, v239
	v_mov_b32_e32 v42, v240
	v_mov_b32_e32 v43, v241
	v_mov_b32_e32 v44, v242
	v_mov_b32_e32 v45, v243
	v_mov_b32_e32 v46, v244
	v_mov_b32_e32 v47, v245
	global_load_dword v210, v[246:247], off offset:-1024
	global_load_dword v211, v[246:247], off offset:-512
	global_load_dword v212, v[246:247], off
	global_load_dword v213, v[246:247], off offset:512
	global_load_dwordx4 v[214:217], v[248:249], off offset:-4096
	global_load_dwordx4 v[238:241], v[248:249], off
	global_load_dwordx4 v[242:245], v[250:251], off offset:-4096
	global_load_dwordx4 v[218:221], v[250:251], off
	global_load_dwordx4 v[222:225], v[252:253], off offset:-4096
	global_load_dwordx4 v[226:229], v[252:253], off
	global_load_dwordx4 v[230:233], v[98:99], off offset:-4096
	global_load_dwordx4 v[234:237], v[98:99], off
	v_add_co_u32_e32 v246, vcc, 0x800, v246
	s_nop 1
	v_addc_co_u32_e32 v247, vcc, 0, v247, vcc
	v_add_co_u32_e32 v248, vcc, 0x10, v248
	s_nop 1
	v_addc_co_u32_e32 v249, vcc, 0, v249, vcc
	v_add_co_u32_e32 v250, vcc, 0x10, v250
	s_nop 1
	v_addc_co_u32_e32 v251, vcc, 0, v251, vcc
	v_add_co_u32_e32 v252, vcc, 0x10, v252
	s_nop 1
	v_addc_co_u32_e32 v253, vcc, 0, v253, vcc
	v_add_co_u32_e32 v98, vcc, 0x10, v98
	s_nop 1
	v_addc_co_u32_e32 v99, vcc, 0, v99, vcc
	v_mov_b32_e32 v56, v16
	v_mov_b32_e32 v16, v18
	v_mov_b32_e32 v59, v20
	v_mov_b32_e32 v60, v24
	v_mov_b32_e32 v61, v28
	v_mov_b32_e32 v62, v32
	v_mov_b32_e32 v63, v36
	v_mov_b32_e32 v57, v40
	v_mov_b32_e32 v58, v44
	v_mov_b32_e32 v28, v25
	v_mov_b32_e32 v36, v33
	v_pk_fma_f32 v[6:7], v[48:49], v[60:61], v[6:7] op_sel_hi:[0,1,1]
	v_pk_fma_f32 v[0:1], v[48:49], v[62:63], v[0:1] op_sel_hi:[0,1,1]
	v_mov_b32_e32 v40, v17
	v_mov_b32_e32 v20, v45
	v_pk_fma_f32 v[4:5], v[48:49], v[56:57], v[4:5] op_sel_hi:[0,1,1]
	v_pk_fma_f32 v[2:3], v[48:49], v[58:59], v[2:3] op_sel_hi:[0,1,1]
	v_mov_b32_e32 v25, v22
	v_mov_b32_e32 v32, v26
	v_mov_b32_e32 v33, v30
	v_mov_b32_e32 v66, v34
	v_mov_b32_e32 v67, v38
	v_mov_b32_e32 v17, v42
	v_mov_b32_e32 v24, v46
	v_pk_fma_f32 v[6:7], v[50:51], v[28:29], v[6:7] op_sel_hi:[0,1,1]
	v_pk_fma_f32 v[0:1], v[50:51], v[36:37], v[0:1] op_sel_hi:[0,1,1]
	v_pk_fma_f32 v[4:5], v[50:51], v[40:41], v[4:5] op_sel_hi:[0,1,1]
	v_pk_fma_f32 v[2:3], v[50:51], v[20:21], v[2:3] op_sel_hi:[0,1,1]
	v_mov_b32_e32 v30, v27
	v_mov_b32_e32 v38, v35
	v_mov_b32_e32 v42, v19
	v_mov_b32_e32 v22, v47
	v_pk_fma_f32 v[6:7], v[52:53], v[32:33], v[6:7] op_sel_hi:[0,1,1]
	v_pk_fma_f32 v[0:1], v[52:53], v[66:67], v[0:1] op_sel_hi:[0,1,1]
	v_pk_fma_f32 v[4:5], v[52:53], v[16:17], v[4:5] op_sel_hi:[0,1,1]
	v_pk_fma_f32 v[2:3], v[52:53], v[24:25], v[2:3] op_sel_hi:[0,1,1]
	v_pk_fma_f32 v[6:7], v[54:55], v[30:31], v[6:7] op_sel_hi:[0,1,1]
	v_pk_fma_f32 v[0:1], v[54:55], v[38:39], v[0:1] op_sel_hi:[0,1,1]
	v_pk_fma_f32 v[4:5], v[54:55], v[42:43], v[4:5] op_sel_hi:[0,1,1]
	v_pk_fma_f32 v[2:3], v[54:55], v[22:23], v[2:3] op_sel_hi:[0,1,1]
	s_add_i32 s4, s4, 1
	s_cmp_eq_u32 s4, 7
	s_cbranch_scc0 .LBB0_316
	s_waitcnt vmcnt(36)
	v_mov_b32_e32 v48, v100
	v_mov_b32_e32 v50, v101
	v_mov_b32_e32 v52, v102
	v_mov_b32_e32 v54, v103
	v_mov_b32_e32 v16, v104
	v_mov_b32_e32 v17, v105
	v_mov_b32_e32 v18, v106
	v_mov_b32_e32 v19, v107
	v_mov_b32_e32 v20, v108
	v_mov_b32_e32 v21, v109
	v_mov_b32_e32 v22, v110
	v_mov_b32_e32 v23, v111
	v_mov_b32_e32 v24, v112
	v_mov_b32_e32 v25, v113
	v_mov_b32_e32 v26, v114
	v_mov_b32_e32 v27, v115
	v_mov_b32_e32 v28, v116
	v_mov_b32_e32 v29, v117
	v_mov_b32_e32 v30, v118
	v_mov_b32_e32 v31, v119
	v_mov_b32_e32 v32, v120
	v_mov_b32_e32 v33, v121
	v_mov_b32_e32 v34, v122
	v_mov_b32_e32 v35, v123
	v_mov_b32_e32 v36, v124
	v_mov_b32_e32 v37, v125
	v_mov_b32_e32 v38, v126
	v_mov_b32_e32 v39, v127
	v_mov_b32_e32 v40, v128
	v_mov_b32_e32 v41, v129
	v_mov_b32_e32 v42, v130
	v_mov_b32_e32 v43, v131
	v_mov_b32_e32 v44, v132
	v_mov_b32_e32 v45, v133
	v_mov_b32_e32 v46, v134
	v_mov_b32_e32 v47, v135
	v_mov_b32_e32 v56, v16
	v_mov_b32_e32 v16, v18
	v_mov_b32_e32 v59, v20
	v_mov_b32_e32 v60, v24
	v_mov_b32_e32 v61, v28
	v_mov_b32_e32 v62, v32
	v_mov_b32_e32 v63, v36
	v_mov_b32_e32 v57, v40
	v_mov_b32_e32 v58, v44
	v_mov_b32_e32 v28, v25
	v_mov_b32_e32 v36, v33
	v_pk_fma_f32 v[6:7], v[48:49], v[60:61], v[6:7] op_sel_hi:[0,1,1]
	v_pk_fma_f32 v[0:1], v[48:49], v[62:63], v[0:1] op_sel_hi:[0,1,1]
	v_mov_b32_e32 v40, v17
	v_mov_b32_e32 v20, v45
	v_pk_fma_f32 v[4:5], v[48:49], v[56:57], v[4:5] op_sel_hi:[0,1,1]
	v_pk_fma_f32 v[2:3], v[48:49], v[58:59], v[2:3] op_sel_hi:[0,1,1]
	v_mov_b32_e32 v25, v22
	v_mov_b32_e32 v32, v26
	v_mov_b32_e32 v33, v30
	v_mov_b32_e32 v66, v34
	v_mov_b32_e32 v67, v38
	v_mov_b32_e32 v17, v42
	v_mov_b32_e32 v24, v46
	v_pk_fma_f32 v[6:7], v[50:51], v[28:29], v[6:7] op_sel_hi:[0,1,1]
	v_pk_fma_f32 v[0:1], v[50:51], v[36:37], v[0:1] op_sel_hi:[0,1,1]
	v_pk_fma_f32 v[4:5], v[50:51], v[40:41], v[4:5] op_sel_hi:[0,1,1]
	v_pk_fma_f32 v[2:3], v[50:51], v[20:21], v[2:3] op_sel_hi:[0,1,1]
	v_mov_b32_e32 v30, v27
	v_mov_b32_e32 v38, v35
	v_mov_b32_e32 v42, v19
	v_mov_b32_e32 v22, v47
	v_pk_fma_f32 v[6:7], v[52:53], v[32:33], v[6:7] op_sel_hi:[0,1,1]
	v_pk_fma_f32 v[0:1], v[52:53], v[66:67], v[0:1] op_sel_hi:[0,1,1]
	v_pk_fma_f32 v[4:5], v[52:53], v[16:17], v[4:5] op_sel_hi:[0,1,1]
	v_pk_fma_f32 v[2:3], v[52:53], v[24:25], v[2:3] op_sel_hi:[0,1,1]
	v_pk_fma_f32 v[6:7], v[54:55], v[30:31], v[6:7] op_sel_hi:[0,1,1]
	v_pk_fma_f32 v[0:1], v[54:55], v[38:39], v[0:1] op_sel_hi:[0,1,1]
	v_pk_fma_f32 v[4:5], v[54:55], v[42:43], v[4:5] op_sel_hi:[0,1,1]
	v_pk_fma_f32 v[2:3], v[54:55], v[22:23], v[2:3] op_sel_hi:[0,1,1]
	s_waitcnt vmcnt(24)
	v_mov_b32_e32 v48, v136
	v_mov_b32_e32 v50, v137
	v_mov_b32_e32 v52, v138
	v_mov_b32_e32 v54, v139
	v_mov_b32_e32 v16, v140
	v_mov_b32_e32 v17, v141
	v_mov_b32_e32 v18, v142
	v_mov_b32_e32 v19, v143
	v_mov_b32_e32 v20, v144
	v_mov_b32_e32 v21, v145
	v_mov_b32_e32 v22, v146
	v_mov_b32_e32 v23, v147
	v_mov_b32_e32 v24, v148
	v_mov_b32_e32 v25, v149
	v_mov_b32_e32 v26, v150
	v_mov_b32_e32 v27, v151
	v_mov_b32_e32 v28, v152
	v_mov_b32_e32 v29, v153
	v_mov_b32_e32 v30, v154
	v_mov_b32_e32 v31, v155
	v_mov_b32_e32 v32, v156
	v_mov_b32_e32 v33, v157
	v_mov_b32_e32 v34, v158
	v_mov_b32_e32 v35, v159
	v_mov_b32_e32 v36, v160
	v_mov_b32_e32 v37, v161
	v_mov_b32_e32 v38, v162
	v_mov_b32_e32 v39, v163
	v_mov_b32_e32 v40, v164
	v_mov_b32_e32 v41, v165
	v_mov_b32_e32 v42, v166
	v_mov_b32_e32 v43, v167
	v_mov_b32_e32 v44, v168
	v_mov_b32_e32 v45, v169
	v_mov_b32_e32 v46, v170
	v_mov_b32_e32 v47, v171
	v_mov_b32_e32 v56, v16
	v_mov_b32_e32 v16, v18
	v_mov_b32_e32 v59, v20
	v_mov_b32_e32 v60, v24
	v_mov_b32_e32 v61, v28
	v_mov_b32_e32 v62, v32
	v_mov_b32_e32 v63, v36
	v_mov_b32_e32 v57, v40
	v_mov_b32_e32 v58, v44
	v_mov_b32_e32 v28, v25
	v_mov_b32_e32 v36, v33
	v_pk_fma_f32 v[6:7], v[48:49], v[60:61], v[6:7] op_sel_hi:[0,1,1]
	v_pk_fma_f32 v[0:1], v[48:49], v[62:63], v[0:1] op_sel_hi:[0,1,1]
	v_mov_b32_e32 v40, v17
	v_mov_b32_e32 v20, v45
	v_pk_fma_f32 v[4:5], v[48:49], v[56:57], v[4:5] op_sel_hi:[0,1,1]
	v_pk_fma_f32 v[2:3], v[48:49], v[58:59], v[2:3] op_sel_hi:[0,1,1]
	v_mov_b32_e32 v25, v22
	v_mov_b32_e32 v32, v26
	v_mov_b32_e32 v33, v30
	v_mov_b32_e32 v66, v34
	v_mov_b32_e32 v67, v38
	v_mov_b32_e32 v17, v42
	v_mov_b32_e32 v24, v46
	v_pk_fma_f32 v[6:7], v[50:51], v[28:29], v[6:7] op_sel_hi:[0,1,1]
	v_pk_fma_f32 v[0:1], v[50:51], v[36:37], v[0:1] op_sel_hi:[0,1,1]
	v_pk_fma_f32 v[4:5], v[50:51], v[40:41], v[4:5] op_sel_hi:[0,1,1]
	v_pk_fma_f32 v[2:3], v[50:51], v[20:21], v[2:3] op_sel_hi:[0,1,1]
	v_mov_b32_e32 v30, v27
	v_mov_b32_e32 v38, v35
	v_mov_b32_e32 v42, v19
	v_mov_b32_e32 v22, v47
	v_pk_fma_f32 v[6:7], v[52:53], v[32:33], v[6:7] op_sel_hi:[0,1,1]
	v_pk_fma_f32 v[0:1], v[52:53], v[66:67], v[0:1] op_sel_hi:[0,1,1]
	v_pk_fma_f32 v[4:5], v[52:53], v[16:17], v[4:5] op_sel_hi:[0,1,1]
	v_pk_fma_f32 v[2:3], v[52:53], v[24:25], v[2:3] op_sel_hi:[0,1,1]
	v_pk_fma_f32 v[6:7], v[54:55], v[30:31], v[6:7] op_sel_hi:[0,1,1]
	v_pk_fma_f32 v[0:1], v[54:55], v[38:39], v[0:1] op_sel_hi:[0,1,1]
	v_pk_fma_f32 v[4:5], v[54:55], v[42:43], v[4:5] op_sel_hi:[0,1,1]
	v_pk_fma_f32 v[2:3], v[54:55], v[22:23], v[2:3] op_sel_hi:[0,1,1]
	s_waitcnt vmcnt(12)
	v_mov_b32_e32 v48, v174
	v_mov_b32_e32 v50, v175
	v_mov_b32_e32 v52, v176
	v_mov_b32_e32 v54, v177
	v_mov_b32_e32 v16, v178
	v_mov_b32_e32 v17, v179
	v_mov_b32_e32 v18, v180
	v_mov_b32_e32 v19, v181
	v_mov_b32_e32 v20, v182
	v_mov_b32_e32 v21, v183
	v_mov_b32_e32 v22, v184
	v_mov_b32_e32 v23, v185
	v_mov_b32_e32 v24, v186
	v_mov_b32_e32 v25, v187
	v_mov_b32_e32 v26, v188
	v_mov_b32_e32 v27, v189
	v_mov_b32_e32 v28, v190
	v_mov_b32_e32 v29, v191
	v_mov_b32_e32 v30, v192
	v_mov_b32_e32 v31, v193
	v_mov_b32_e32 v32, v194
	v_mov_b32_e32 v33, v195
	v_mov_b32_e32 v34, v196
	v_mov_b32_e32 v35, v197
	v_mov_b32_e32 v36, v198
	v_mov_b32_e32 v37, v199
	v_mov_b32_e32 v38, v200
	v_mov_b32_e32 v39, v201
	v_mov_b32_e32 v40, v202
	v_mov_b32_e32 v41, v203
	v_mov_b32_e32 v42, v204
	v_mov_b32_e32 v43, v205
	v_mov_b32_e32 v44, v206
	v_mov_b32_e32 v45, v207
	v_mov_b32_e32 v46, v208
	v_mov_b32_e32 v47, v209
	v_mov_b32_e32 v56, v16
	v_mov_b32_e32 v16, v18
	v_mov_b32_e32 v59, v20
	v_mov_b32_e32 v60, v24
	v_mov_b32_e32 v61, v28
	v_mov_b32_e32 v62, v32
	v_mov_b32_e32 v63, v36
	v_mov_b32_e32 v57, v40
	v_mov_b32_e32 v58, v44
	v_mov_b32_e32 v28, v25
	v_mov_b32_e32 v36, v33
	v_pk_fma_f32 v[6:7], v[48:49], v[60:61], v[6:7] op_sel_hi:[0,1,1]
	v_pk_fma_f32 v[0:1], v[48:49], v[62:63], v[0:1] op_sel_hi:[0,1,1]
	v_mov_b32_e32 v40, v17
	v_mov_b32_e32 v20, v45
	v_pk_fma_f32 v[4:5], v[48:49], v[56:57], v[4:5] op_sel_hi:[0,1,1]
	v_pk_fma_f32 v[2:3], v[48:49], v[58:59], v[2:3] op_sel_hi:[0,1,1]
	v_mov_b32_e32 v25, v22
	v_mov_b32_e32 v32, v26
	v_mov_b32_e32 v33, v30
	v_mov_b32_e32 v66, v34
	v_mov_b32_e32 v67, v38
	v_mov_b32_e32 v17, v42
	v_mov_b32_e32 v24, v46
	v_pk_fma_f32 v[6:7], v[50:51], v[28:29], v[6:7] op_sel_hi:[0,1,1]
	v_pk_fma_f32 v[0:1], v[50:51], v[36:37], v[0:1] op_sel_hi:[0,1,1]
	v_pk_fma_f32 v[4:5], v[50:51], v[40:41], v[4:5] op_sel_hi:[0,1,1]
	v_pk_fma_f32 v[2:3], v[50:51], v[20:21], v[2:3] op_sel_hi:[0,1,1]
	v_mov_b32_e32 v30, v27
	v_mov_b32_e32 v38, v35
	v_mov_b32_e32 v42, v19
	v_mov_b32_e32 v22, v47
	v_pk_fma_f32 v[6:7], v[52:53], v[32:33], v[6:7] op_sel_hi:[0,1,1]
	v_pk_fma_f32 v[0:1], v[52:53], v[66:67], v[0:1] op_sel_hi:[0,1,1]
	v_pk_fma_f32 v[4:5], v[52:53], v[16:17], v[4:5] op_sel_hi:[0,1,1]
	v_pk_fma_f32 v[2:3], v[52:53], v[24:25], v[2:3] op_sel_hi:[0,1,1]
	v_pk_fma_f32 v[6:7], v[54:55], v[30:31], v[6:7] op_sel_hi:[0,1,1]
	v_pk_fma_f32 v[0:1], v[54:55], v[38:39], v[0:1] op_sel_hi:[0,1,1]
	v_pk_fma_f32 v[4:5], v[54:55], v[42:43], v[4:5] op_sel_hi:[0,1,1]
	v_pk_fma_f32 v[2:3], v[54:55], v[22:23], v[2:3] op_sel_hi:[0,1,1]
	s_waitcnt vmcnt(0)
	v_mov_b32_e32 v48, v210
	v_mov_b32_e32 v50, v211
	v_mov_b32_e32 v52, v212
	v_mov_b32_e32 v54, v213
	v_mov_b32_e32 v16, v214
	v_mov_b32_e32 v17, v215
	v_mov_b32_e32 v18, v216
	v_mov_b32_e32 v19, v217
	v_mov_b32_e32 v20, v218
	v_mov_b32_e32 v21, v219
	v_mov_b32_e32 v22, v220
	v_mov_b32_e32 v23, v221
	v_mov_b32_e32 v24, v222
	v_mov_b32_e32 v25, v223
	v_mov_b32_e32 v26, v224
	v_mov_b32_e32 v27, v225
	v_mov_b32_e32 v28, v226
	v_mov_b32_e32 v29, v227
	v_mov_b32_e32 v30, v228
	v_mov_b32_e32 v31, v229
	v_mov_b32_e32 v32, v230
	v_mov_b32_e32 v33, v231
	v_mov_b32_e32 v34, v232
	v_mov_b32_e32 v35, v233
	v_mov_b32_e32 v36, v234
	v_mov_b32_e32 v37, v235
	v_mov_b32_e32 v38, v236
	v_mov_b32_e32 v39, v237
	v_mov_b32_e32 v40, v238
	v_mov_b32_e32 v41, v239
	v_mov_b32_e32 v42, v240
	v_mov_b32_e32 v43, v241
	v_mov_b32_e32 v44, v242
	v_mov_b32_e32 v45, v243
	v_mov_b32_e32 v46, v244
	v_mov_b32_e32 v47, v245
	v_mov_b32_e32 v56, v16
	v_mov_b32_e32 v16, v18
	v_mov_b32_e32 v59, v20
	v_mov_b32_e32 v60, v24
	v_mov_b32_e32 v61, v28
	v_mov_b32_e32 v62, v32
	v_mov_b32_e32 v63, v36
	v_mov_b32_e32 v57, v40
	v_mov_b32_e32 v58, v44
	v_mov_b32_e32 v28, v25
	v_mov_b32_e32 v36, v33
	v_pk_fma_f32 v[6:7], v[48:49], v[60:61], v[6:7] op_sel_hi:[0,1,1]
	v_pk_fma_f32 v[0:1], v[48:49], v[62:63], v[0:1] op_sel_hi:[0,1,1]
	v_mov_b32_e32 v40, v17
	v_mov_b32_e32 v20, v45
	v_pk_fma_f32 v[4:5], v[48:49], v[56:57], v[4:5] op_sel_hi:[0,1,1]
	v_pk_fma_f32 v[2:3], v[48:49], v[58:59], v[2:3] op_sel_hi:[0,1,1]
	v_mov_b32_e32 v25, v22
	v_mov_b32_e32 v32, v26
	v_mov_b32_e32 v33, v30
	v_mov_b32_e32 v66, v34
	v_mov_b32_e32 v67, v38
	v_mov_b32_e32 v17, v42
	v_mov_b32_e32 v24, v46
	v_pk_fma_f32 v[6:7], v[50:51], v[28:29], v[6:7] op_sel_hi:[0,1,1]
	v_pk_fma_f32 v[0:1], v[50:51], v[36:37], v[0:1] op_sel_hi:[0,1,1]
	v_pk_fma_f32 v[4:5], v[50:51], v[40:41], v[4:5] op_sel_hi:[0,1,1]
	v_pk_fma_f32 v[2:3], v[50:51], v[20:21], v[2:3] op_sel_hi:[0,1,1]
	v_mov_b32_e32 v30, v27
	v_mov_b32_e32 v38, v35
	v_mov_b32_e32 v42, v19
	v_mov_b32_e32 v22, v47
	v_pk_fma_f32 v[6:7], v[52:53], v[32:33], v[6:7] op_sel_hi:[0,1,1]
	v_pk_fma_f32 v[0:1], v[52:53], v[66:67], v[0:1] op_sel_hi:[0,1,1]
	v_pk_fma_f32 v[4:5], v[52:53], v[16:17], v[4:5] op_sel_hi:[0,1,1]
	v_pk_fma_f32 v[2:3], v[52:53], v[24:25], v[2:3] op_sel_hi:[0,1,1]
	v_pk_fma_f32 v[6:7], v[54:55], v[30:31], v[6:7] op_sel_hi:[0,1,1]
	v_pk_fma_f32 v[0:1], v[54:55], v[38:39], v[0:1] op_sel_hi:[0,1,1]
	v_pk_fma_f32 v[4:5], v[54:55], v[42:43], v[4:5] op_sel_hi:[0,1,1]
	v_pk_fma_f32 v[2:3], v[54:55], v[22:23], v[2:3] op_sel_hi:[0,1,1]
	s_lshl_b32 s2, s28, 2
	s_andn2_b32 s2, s2, 63
	v_or_b32_e32 v8, s2, v12
	v_ashrrev_i32_e32 v9, 31, v8
	s_lshl_b32 s3, s28, 6
	v_lshl_add_u64 v[8:9], v[8:9], 2, s[20:21]
	s_and_b32 s3, s3, 0x3c0
	global_load_dword v20, v[8:9], off
	v_add_u32_e32 v8, s3, v13
	v_ashrrev_i32_e32 v9, 31, v8
	v_lshl_add_u64 v[16:17], v[8:9], 2, s[0:1]
	global_load_dwordx4 v[8:11], v[16:17], off
	s_nop 0
	global_load_dwordx4 v[16:19], v[16:17], off offset:16
	v_mov_b32_e32 v22, v173
	v_add_u32_e32 v21, 0x400, v14
	s_lshl_b32 s66, s3, 1
	s_add_i32 s28, s28, s27
	s_add_i32 s10, s10, s11
	s_add_i32 s22, s22, s23
	s_cmpk_gt_i32 s28, 0x7f
	s_waitcnt vmcnt(2)
	v_mul_f32_e32 v4, v4, v20
	v_mul_f32_e32 v5, v5, v20
	v_mul_f32_e32 v0, v0, v20
	v_mul_f32_e32 v2, v2, v20
	v_mul_f32_e32 v3, v3, v20
	v_mul_f32_e32 v6, v6, v20
	v_mul_f32_e32 v7, v7, v20
	v_mul_f32_e32 v1, v1, v20
	s_waitcnt vmcnt(1)
	v_mul_f32_e32 v4, v4, v8
	v_mul_f32_e32 v5, v5, v9
	s_waitcnt vmcnt(0)
	v_mul_f32_e32 v0, v0, v18
	v_mul_f32_e32 v2, v2, v10
	v_mul_f32_e32 v3, v3, v11
	v_mul_f32_e32 v6, v6, v16
	v_mul_f32_e32 v7, v7, v17
	v_mul_f32_e32 v1, v1, v19
	ds_write2_b32 v14, v4, v5 offset1:65
	ds_write2_b32 v14, v2, v3 offset0:130 offset1:195
	ds_write2_b32 v21, v6, v7 offset0:4 offset1:69
	ds_write_b32 v14, v0 offset:1560
	ds_write_b32 v15, v1
	s_waitcnt lgkmcnt(0)
	s_barrier
	s_nop 0
	v_ashrrev_i32_e32 v0, 3, v22
	v_lshlrev_b32_e32 v1, 3, v22
	v_add_u32_e32 v8, s2, v0
	v_and_b32_e32 v1, 56, v1
	v_ashrrev_i32_e32 v3, 31, v8
	v_lshlrev_b32_e32 v2, 2, v0
	v_mul_u32_u24_e32 v0, 0x104, v1
	v_lshrrev_b32_e32 v5, 23, v3
	v_add3_u32 v4, 0, v0, v2
	v_add_u32_e32 v9, v8, v5
	v_add_u32_e32 v6, 0x400, v4
	v_and_b32_e32 v9, 0xfffffe00, v9
	v_lshlrev_b32_e32 v64, 1, v1
	ds_read2_b32 v[0:1], v4 offset1:65
	ds_read2_b32 v[2:3], v4 offset0:130 offset1:195
	ds_read2_b32 v[4:5], v6 offset0:4 offset1:69
	ds_read2_b32 v[6:7], v6 offset0:134 offset1:199
	v_sub_u32_e32 v8, v8, v9
	v_ashrrev_i32_e32 v9, 31, v8
	v_lshlrev_b64 v[8:9], 11, v[8:9]
	v_lshl_add_u64 v[8:9], s[24:25], 0, v[8:9]
	v_lshl_add_u64 v[8:9], v[8:9], 0, s[66:67]
	s_waitcnt lgkmcnt(3)
	v_cvt_pk_bf16_f32 v0, v0, v1
	s_waitcnt lgkmcnt(2)
	v_cvt_pk_bf16_f32 v1, v2, v3
	s_waitcnt lgkmcnt(1)
	v_cvt_pk_bf16_f32 v2, v4, v5
	s_waitcnt lgkmcnt(0)
	v_cvt_pk_bf16_f32 v3, v6, v7
	v_lshl_add_u64 v[4:5], v[8:9], 0, v[64:65]
	global_store_dwordx4 v[4:5], v[0:3], off
	s_barrier
	s_cbranch_scc0 .LBB0_315
